# stack: the split grid sync / early-invalidate seams (all66) with the attention main loop at its VALU floor (half-row rescale decision, SGPR-base DMA sources, preheader rescale address)
# speedup vs baseline: 1.0025x; 1.0023x over previous
; #define WAIT_BAR(N) asm volatile("s_waitcnt vmcnt(" #N ") lgkmcnt(0)\n\ts_barrier":::"memory")
;   #define DMA_K(t,slot) glds16(ksrc+(long)(t)*KVBLK*PD,(unsigned)__builtin_amdgcn_readfirstlane(kdst+(slot)))
;   #define DMA_V(t,slot) glds16(vsrc+(long)(t)*KVBLK*PD,(unsigned)__builtin_amdgcn_readfirstlane(vdst+(slot)))
;   #define CMASK(P0,P1,t) do{int jb_=(t)-(NT-4); if(jb_>=0)cmask(P0,P1,jb_,qrel,hi);}while(0)
;   #define START(P0,P1) do{ const float rm=rowmax(P0,P1); resc=false; \
;     { const float dl=rm; mhat=fadd_s(mhat,dl); \
;       _Pragma("unroll") for(int r=0;r<16;++r){P0[r]=fsub_s(P0[r],dl);P1[r]=fsub_s(P1[r],dl);} \
;       _Pragma("unroll") for(int r=0;r<16;++r)negm[r]=-mhat; asm volatile("":"+v"(negm)); } \
;     _Pragma("unroll") for(int r=0;r<16;++r)P0[r]=__builtin_amdgcn_exp2f(P0[r]); }while(0)
;   #define ROT() do{sl_prev=sl_cur;sl_cur=sl_next;sl_next=(sl_next==(NSLOT-1)*SLOTB)?0:sl_next+SLOTB;}while(0)
;   #define CMASK(P0,P1,t) do{}while(0)
;   #define CMASK(P0,P1,t) do{int jb_=(t)-(NT-4); if(jb_>=0)cmask(P0,P1,jb_,qrel,hi);}while(0)
; template<int THRL> __device__ __forceinline__ void attn_unit(int b,int h,int qb,const bf16*Q,const bf16*__restrict__ K,const bf16*__restrict__ V,bf16*O,char*shm,const int wid){
;     ...
;   f32x16 pA0,pA1,pB0,pB1;
;   int sl_prev=0,sl_cur=0,sl_next=SLOTB;
;     ...
;   DMA_K(2,2*SLOTB);
;   WAIT_BAR(3);
;   qkt(pA0,pA1,Kbase,qr,negm,r32,hi);asm volatile("s_nop 15\n\ts_nop 7":"+v"(pA0),"+v"(pA1));CMASK(pA0,pA1,0);
;   START(pA0,pA1);
;   _Pragma("unroll") for(int r=0;r<16;++r)pA1[r]=__builtin_amdgcn_exp2f(pA1[r]);
;   WAIT_BAR(0);
;   DMA_K(3,0);DMA_V(1,SLOTB);
;   ROT();
;   kload8(kf,kp0+sl_cur);
;   WAIT_BAR(2);
;     ...
;   int t=1;
;     ...
;   for(;t+5<NT;t+=2){
.LBB0_1545:
	v_lshlrev_b32_e32 v0, 1, v210
	v_and_b32_e32 v217, 32, v0
	v_lshlrev_b32_e32 v0, 4, v210
	v_and_b32_e32 v0, 0xc0, v0
	v_lshl_or_b32 v215, v213, 8, v0
	v_add_u32_e32 v0, 0, v217
	v_add3_u32 v221, v0, v214, v215
	v_max3_f32 v0, v18, v19, v2
	v_max3_f32 v36, v20, v21, v3
	s_sub_i32 s3, 0x1000, s36
	v_max3_f32 v0, v0, v4, v5
	v_max3_f32 v36, v36, v24, v25
	s_lshr_b32 s3, s3, 6
	v_max3_f32 v0, v0, v22, v23
	v_max3_f32 v36, v36, v8, v9
	s_cmp_lg_u32 0, -1
	v_max3_f32 v0, v0, v6, v7
	v_max3_f32 v36, v36, v28, v29
	v_lshl_add_u64 v[198:199], v[34:35], 0, s[22:23]
	v_max3_f32 v0, v0, v26, v27
	v_max3_f32 v36, v36, v12, v13
	s_mov_b32 s8, 1
	v_max3_f32 v0, v0, v10, v11
	v_max3_f32 v36, v36, v32, v33
	s_mov_b32 s38, 0
	v_max3_f32 v0, v0, v30, v31
	v_max3_f32 v36, v36, v16, v17
	v_lshlrev_b32_e32 v222, 4, v213
	v_max3_f32 v0, v0, v14, v15
	s_nop 0
	v_max_f32_e32 v0, v0, v36
	s_nop 0
	v_mov_b32_e32 v36, v0
	s_nop 1
	v_permlane32_swap_b32_e32 v0, v36
	v_max_f32_e32 v0, v0, v36
	s_nop 0
	v_add_f32_e32 v219, v1, v0
	v_sub_f32_e32 v2, v2, v0
	v_sub_f32_e32 v3, v3, v0
	v_sub_f32_e32 v18, v18, v0
	v_sub_f32_e32 v19, v19, v0
	v_sub_f32_e32 v20, v20, v0
	s_nop 0
	v_xor_b32_e32 v48, 0x80000000, v219
	v_mov_b32_e32 v49, v48
	v_mov_b32_e32 v50, v48
	v_mov_b32_e32 v51, v48
	v_mov_b32_e32 v52, v48
	v_mov_b32_e32 v53, v48
	v_mov_b32_e32 v54, v48
	v_mov_b32_e32 v55, v48
	v_mov_b32_e32 v56, v48
	v_mov_b32_e32 v57, v48
	v_mov_b32_e32 v58, v48
	v_mov_b32_e32 v59, v48
	v_mov_b32_e32 v60, v48
	v_mov_b32_e32 v61, v48
	v_mov_b32_e32 v62, v48
	v_mov_b32_e32 v63, v48
	s_waitcnt vmcnt(0) lgkmcnt(0)
	s_barrier
	v_exp_f32_e32 v64, v2
	v_exp_f32_e32 v65, v3
	v_lshl_add_u64 v[2:3], v[196:197], 0, s[20:21]
	s_mov_b32 s9, m0
	s_mov_b32 m0, s46
	s_nop 0
	global_load_lds_dwordx4 v[2:3], off
	s_mov_b32 m0, s9
	s_cselect_b32 s9, 0, 0
	s_add_i32 s9, s9, s45
	s_add_i32 s9, s9, 0x8000
	s_mov_b32 s13, m0
	s_mov_b32 m0, s9
	s_nop 0
	global_load_lds_dwordx4 v[198:199], off
	s_mov_b32 m0, s13
	ds_read_b128 v[188:191], v220 offset:8192
	ds_read_b128 v[184:187], v220 offset:8704
	ds_read_b128 v[180:183], v220 offset:10240
	ds_read_b128 v[176:179], v220 offset:10752
	ds_read_b128 v[172:175], v220 offset:12288
	ds_read_b128 v[168:171], v220 offset:12800
	ds_read_b128 v[164:167], v220 offset:14336
	ds_read_b128 v[160:163], v220 offset:14848
	v_sub_f32_e32 v4, v4, v0
	v_sub_f32_e32 v21, v21, v0
	v_sub_f32_e32 v5, v5, v0
	v_sub_f32_e32 v22, v22, v0
	v_sub_f32_e32 v6, v6, v0
	v_sub_f32_e32 v23, v23, v0
	v_sub_f32_e32 v7, v7, v0
	v_sub_f32_e32 v24, v24, v0
	v_sub_f32_e32 v8, v8, v0
	v_sub_f32_e32 v25, v25, v0
	v_sub_f32_e32 v9, v9, v0
	v_sub_f32_e32 v26, v26, v0
	v_sub_f32_e32 v10, v10, v0
	v_sub_f32_e32 v27, v27, v0
	v_sub_f32_e32 v11, v11, v0
	v_sub_f32_e32 v28, v28, v0
	v_sub_f32_e32 v12, v12, v0
	v_sub_f32_e32 v29, v29, v0
	v_sub_f32_e32 v13, v13, v0
	v_sub_f32_e32 v30, v30, v0
	v_sub_f32_e32 v14, v14, v0
	v_sub_f32_e32 v31, v31, v0
	v_sub_f32_e32 v15, v15, v0
	v_sub_f32_e32 v32, v32, v0
	v_sub_f32_e32 v16, v16, v0
	v_sub_f32_e32 v33, v33, v0
	v_sub_f32_e32 v0, v17, v0
	v_exp_f32_e32 v80, v18
	v_exp_f32_e32 v81, v19
	v_exp_f32_e32 v82, v20
	v_exp_f32_e32 v83, v21
	v_exp_f32_e32 v84, v22
	v_exp_f32_e32 v85, v23
	v_exp_f32_e32 v86, v24
	v_exp_f32_e32 v87, v25
	v_exp_f32_e32 v88, v26
	v_exp_f32_e32 v89, v27
	v_exp_f32_e32 v90, v28
	v_exp_f32_e32 v91, v29
	v_exp_f32_e32 v92, v30
	v_exp_f32_e32 v93, v31
	v_exp_f32_e32 v94, v32
	v_exp_f32_e32 v95, v33
	v_exp_f32_e32 v66, v4
	v_exp_f32_e32 v67, v5
	v_exp_f32_e32 v68, v6
	v_exp_f32_e32 v69, v7
	v_exp_f32_e32 v70, v8
	v_exp_f32_e32 v71, v9
	v_exp_f32_e32 v72, v10
	v_exp_f32_e32 v73, v11
	v_exp_f32_e32 v74, v12
	v_exp_f32_e32 v75, v13
	v_exp_f32_e32 v76, v14
	v_exp_f32_e32 v77, v15
	v_exp_f32_e32 v78, v16
	v_exp_f32_e32 v79, v0
	s_waitcnt vmcnt(2) lgkmcnt(0)
	s_barrier
	s_andn2_b64 vcc, exec, s[6:7]
	v_cmp_gt_u32_e64 s[6:7], 32, v210
	s_cbranch_vccnz .LBB0_1561
	v_mov_b32_e32 v14, v1
	v_mov_b32_e32 v15, v1
	v_lshl_add_u64 v[200:201], v[34:35], 0, s[20:21]
	v_mov_b32_e32 v0, v1
	v_mov_b32_e32 v2, v1
	v_mov_b32_e32 v3, v1
	v_mov_b32_e32 v4, v1
	v_mov_b32_e32 v5, v1
	v_mov_b32_e32 v6, v1
	v_mov_b32_e32 v7, v1
	v_mov_b32_e32 v8, v1
	v_mov_b32_e32 v9, v1
	v_mov_b32_e32 v10, v1
	v_mov_b32_e32 v11, v1
	v_mov_b32_e32 v12, v1
	v_mov_b32_e32 v13, v1
	v_mov_b64_e32 v[46:47], v[14:15]
	v_mov_b64_e32 v[30:31], v[14:15]
	v_lshl_add_u32 v204, v212, 2, s48
	v_lshl_add_u64 v[202:203], v[196:197], 0, s[24:25]
	s_mov_b32 s8, 0
	s_movk_i32 s38, 0x4000
	s_movk_i32 s40, 0x2000
	v_mov_b32_e32 v223, 0
	s_mov_b32 s39, 6
	v_readfirstlane_b32 s88, v202
	v_readfirstlane_b32 s89, v203
	v_readfirstlane_b32 s90, v200
	v_readfirstlane_b32 s91, v201
	v_add_u32_e32 v226, s48, v222
	s_nop 3
	v_subrev_u32_e32 v224, s88, v202
	v_subrev_u32_e32 v225, s90, v200
	v_mov_b64_e32 v[44:45], v[12:13]
	v_mov_b64_e32 v[42:43], v[10:11]
	v_mov_b64_e32 v[40:41], v[8:9]
	v_mov_b64_e32 v[38:39], v[6:7]
	v_mov_b64_e32 v[36:37], v[4:5]
	v_mov_b64_e32 v[34:35], v[2:3]
	v_mov_b64_e32 v[32:33], v[0:1]
	v_mov_b64_e32 v[28:29], v[12:13]
	v_mov_b64_e32 v[26:27], v[10:11]
	v_mov_b64_e32 v[24:25], v[8:9]
	v_mov_b64_e32 v[22:23], v[6:7]
	v_mov_b64_e32 v[20:21], v[4:5]
	v_mov_b64_e32 v[18:19], v[2:3]
	v_mov_b64_e32 v[16:17], v[0:1]
	.p2align 6
